# gated-residual GEMM epilogues (out-proj and down-proj) software-pipelined: gates loaded once, 3 groups of x loads in flight, counted vmcnt
# speedup vs baseline: 1.4144x; 1.0247x over previous
;     __device__ __forceinline__ void operator()(const f32x4 (&acc)[2][2][4][2], const Unit& u, int wr, int wc, int fr, int fq) const {
;         const int b = u.pm / 33, tb = u.pm - b * 33;
;         const bool isctx = (tb == 0);
;         const float* gate = mod + (size_t)(isctx ? 4 : b) * 6144 + gidx * 1024;
;         const size_t row0 = isctx ? (size_t)b * CTX : (size_t)b * SEQ + (size_t)(tb - 1) * 256;
;         const float* src = isctx ? cin : xin; float* dst = isctx ? cout : xout;
;         const int col0 = u.pn * 256 + wc * 32 + 4 * fq;
; #pragma unroll
;         for (int ai = 0; ai < 2; ++ai)
; #pragma unroll
;             for (int m = 0; m < 4; ++m) {
;                 const size_t ro = (row0 + ai * 128 + wr * 64 + m * 16 + fr) * DM;
; #pragma unroll
;                 for (int bj = 0; bj < 2; ++bj)
; #pragma unroll
;                     for (int n = 0; n < 2; ++n) {
;                         const int c = col0 + bj * 128 + n * 16;
;                         const f32x4 gv = *(const f32x4*)(gate + c); const f32x4 xv = *(const f32x4*)(src + ro + c);
;                         *(f32x4*)(dst + ro + c) = xv + gv * acc[ai][bj][m][n];
;                     }
;                 asm volatile("" ::: "memory");
;             }
;     }
.LBB0_1086:
	s_add_u32 s5, s6, s44
	v_lshl_or_b32 v190, s58, 8, v141
	v_lshl_add_u64 v[152:153], v[146:147], 0, s[42:43]
	s_addc_u32 s23, s7, s45
	v_lshlrev_b64 v[152:153], 12, v[152:153]
	v_ashrrev_i32_e32 v191, 31, v190
	s_add_u32 s40, s5, 0x2000
	v_lshl_add_u64 v[154:155], s[46:47], 0, v[152:153]
	v_lshlrev_b64 v[156:157], 2, v[190:191]
	s_addc_u32 s41, s23, 0
	v_lshl_add_u64 v[154:155], v[154:155], 0, v[156:157]
	v_lshl_add_u64 v[158:159], s[40:41], 0, v[156:157]
	v_lshl_add_u64 v[152:153], s[38:39], 0, v[152:153]
	v_lshl_add_u64 v[152:153], v[152:153], 0, v[156:157]
	s_mov_b32 s58, s4
	s_mov_b64 s[42:43], s[36:37]
	global_load_dwordx4 v[182:185], v[158:159], off
	global_load_dwordx4 v[186:189], v[158:159], off offset:64
	global_load_dwordx4 v[190:193], v[158:159], off offset:512
	global_load_dwordx4 v[194:197], v[158:159], off offset:576
	global_load_dwordx4 v[198:201], v[154:155], off
	global_load_dwordx4 v[202:205], v[154:155], off offset:64
	global_load_dwordx4 v[206:209], v[154:155], off offset:512
	global_load_dwordx4 v[210:213], v[154:155], off offset:576
	s_mov_b64 s[38:39], 0x10000
	v_lshl_add_u64 v[156:157], v[154:155], 0, s[38:39]
	global_load_dwordx4 v[214:217], v[156:157], off
	global_load_dwordx4 v[218:221], v[156:157], off offset:64
	global_load_dwordx4 v[222:225], v[156:157], off offset:512
	global_load_dwordx4 v[226:229], v[156:157], off offset:576
	s_mov_b64 s[38:39], 0x20000
	v_lshl_add_u64 v[156:157], v[154:155], 0, s[38:39]
	global_load_dwordx4 v[230:233], v[156:157], off
	global_load_dwordx4 v[234:237], v[156:157], off offset:64
	global_load_dwordx4 v[238:241], v[156:157], off offset:512
	global_load_dwordx4 v[242:245], v[156:157], off offset:576
	s_waitcnt vmcnt(8)
	v_pk_fma_f32 v[126:127], v[126:127], v[182:183], v[198:199]
	v_pk_fma_f32 v[128:129], v[128:129], v[184:185], v[200:201]
	v_pk_fma_f32 v[122:123], v[122:123], v[186:187], v[202:203]
	v_pk_fma_f32 v[124:125], v[124:125], v[188:189], v[204:205]
	v_pk_fma_f32 v[118:119], v[118:119], v[190:191], v[206:207]
	v_pk_fma_f32 v[120:121], v[120:121], v[192:193], v[208:209]
	v_pk_fma_f32 v[110:111], v[110:111], v[194:195], v[210:211]
	v_pk_fma_f32 v[112:113], v[112:113], v[196:197], v[212:213]
	global_store_dwordx4 v[152:153], v[126:129], off
	global_store_dwordx4 v[152:153], v[122:125], off offset:64
	global_store_dwordx4 v[152:153], v[118:121], off offset:512
	global_store_dwordx4 v[152:153], v[110:113], off offset:576
	s_mov_b64 s[38:39], 0x30000
	v_lshl_add_u64 v[156:157], v[154:155], 0, s[38:39]
	global_load_dwordx4 v[198:201], v[156:157], off
	global_load_dwordx4 v[202:205], v[156:157], off offset:64
	global_load_dwordx4 v[206:209], v[156:157], off offset:512
	global_load_dwordx4 v[210:213], v[156:157], off offset:576
	s_waitcnt vmcnt(12)
	s_mov_b64 s[38:39], 0x10000
	v_lshl_add_u64 v[158:159], v[152:153], 0, s[38:39]
	v_pk_fma_f32 v[114:115], v[114:115], v[182:183], v[214:215]
	v_pk_fma_f32 v[116:117], v[116:117], v[184:185], v[216:217]
	v_pk_fma_f32 v[106:107], v[106:107], v[186:187], v[218:219]
	v_pk_fma_f32 v[108:109], v[108:109], v[188:189], v[220:221]
	v_pk_fma_f32 v[102:103], v[102:103], v[190:191], v[222:223]
	v_pk_fma_f32 v[104:105], v[104:105], v[192:193], v[224:225]
	v_pk_fma_f32 v[94:95], v[94:95], v[194:195], v[226:227]
	v_pk_fma_f32 v[96:97], v[96:97], v[196:197], v[228:229]
	global_store_dwordx4 v[158:159], v[114:117], off
	global_store_dwordx4 v[158:159], v[106:109], off offset:64
	global_store_dwordx4 v[158:159], v[102:105], off offset:512
	global_store_dwordx4 v[158:159], v[94:97], off offset:576
	s_mov_b64 s[38:39], 0x80000
	v_lshl_add_u64 v[156:157], v[154:155], 0, s[38:39]
	global_load_dwordx4 v[214:217], v[156:157], off
	global_load_dwordx4 v[218:221], v[156:157], off offset:64
	global_load_dwordx4 v[222:225], v[156:157], off offset:512
	global_load_dwordx4 v[226:229], v[156:157], off offset:576
	s_waitcnt vmcnt(16)
	s_mov_b64 s[38:39], 0x20000
	v_lshl_add_u64 v[158:159], v[152:153], 0, s[38:39]
	v_pk_fma_f32 v[98:99], v[98:99], v[182:183], v[230:231]
	v_pk_fma_f32 v[100:101], v[100:101], v[184:185], v[232:233]
	v_pk_fma_f32 v[90:91], v[90:91], v[186:187], v[234:235]
	v_pk_fma_f32 v[92:93], v[92:93], v[188:189], v[236:237]
	v_pk_fma_f32 v[86:87], v[86:87], v[190:191], v[238:239]
	v_pk_fma_f32 v[88:89], v[88:89], v[192:193], v[240:241]
	v_pk_fma_f32 v[78:79], v[78:79], v[194:195], v[242:243]
	v_pk_fma_f32 v[80:81], v[80:81], v[196:197], v[244:245]
	global_store_dwordx4 v[158:159], v[98:101], off
	global_store_dwordx4 v[158:159], v[90:93], off offset:64
	global_store_dwordx4 v[158:159], v[86:89], off offset:512
	global_store_dwordx4 v[158:159], v[78:81], off offset:576
	s_mov_b64 s[38:39], 0x90000
	v_lshl_add_u64 v[156:157], v[154:155], 0, s[38:39]
	global_load_dwordx4 v[230:233], v[156:157], off
	global_load_dwordx4 v[234:237], v[156:157], off offset:64
	global_load_dwordx4 v[238:241], v[156:157], off offset:512
	global_load_dwordx4 v[242:245], v[156:157], off offset:576
	s_waitcnt vmcnt(16)
;     __device__ __forceinline__ void operator()(const f32x4 (&acc)[2][2][4][2], const Unit& u, int wr, int wc, int fr, int fq) const {
;         const int b = u.pm / 33, tb = u.pm - b * 33;
;         const bool isctx = (tb == 0);
;         const float* gate = mod + (size_t)(isctx ? 4 : b) * 6144 + gidx * 1024;
;         const size_t row0 = isctx ? (size_t)b * CTX : (size_t)b * SEQ + (size_t)(tb - 1) * 256;
;         const float* src = isctx ? cin : xin; float* dst = isctx ? cout : xout;
;         const int col0 = u.pn * 256 + wc * 32 + 4 * fq;
; #pragma unroll
;         for (int ai = 0; ai < 2; ++ai)
; #pragma unroll
;             for (int m = 0; m < 4; ++m) {
;                 const size_t ro = (row0 + ai * 128 + wr * 64 + m * 16 + fr) * DM;
; #pragma unroll
;                 for (int bj = 0; bj < 2; ++bj)
; #pragma unroll
;                     for (int n = 0; n < 2; ++n) {
;                         const int c = col0 + bj * 128 + n * 16;
;                         const f32x4 gv = *(const f32x4*)(gate + c); const f32x4 xv = *(const f32x4*)(src + ro + c);
;                         *(f32x4*)(dst + ro + c) = xv + gv * acc[ai][bj][m][n];
;                     }
;                 asm volatile("" ::: "memory");
;             }
;     }
	s_mov_b64 s[38:39], 0x30000
	v_lshl_add_u64 v[158:159], v[152:153], 0, s[38:39]
	v_pk_fma_f32 v[82:83], v[82:83], v[182:183], v[198:199]
	v_pk_fma_f32 v[84:85], v[84:85], v[184:185], v[200:201]
	v_pk_fma_f32 v[74:75], v[74:75], v[186:187], v[202:203]
	v_pk_fma_f32 v[76:77], v[76:77], v[188:189], v[204:205]
	v_pk_fma_f32 v[70:71], v[70:71], v[190:191], v[206:207]
	v_pk_fma_f32 v[72:73], v[72:73], v[192:193], v[208:209]
	v_pk_fma_f32 v[66:67], v[66:67], v[194:195], v[210:211]
	v_pk_fma_f32 v[68:69], v[68:69], v[196:197], v[212:213]
	global_store_dwordx4 v[158:159], v[82:85], off
	global_store_dwordx4 v[158:159], v[74:77], off offset:64
	global_store_dwordx4 v[158:159], v[70:73], off offset:512
	global_store_dwordx4 v[158:159], v[66:69], off offset:576
	s_mov_b64 s[38:39], 0xa0000
	v_lshl_add_u64 v[156:157], v[154:155], 0, s[38:39]
	global_load_dwordx4 v[198:201], v[156:157], off
	global_load_dwordx4 v[202:205], v[156:157], off offset:64
	global_load_dwordx4 v[206:209], v[156:157], off offset:512
	global_load_dwordx4 v[210:213], v[156:157], off offset:576
	s_waitcnt vmcnt(16)
	s_mov_b64 s[38:39], 0x80000
	v_lshl_add_u64 v[158:159], v[152:153], 0, s[38:39]
	v_pk_fma_f32 v[62:63], v[62:63], v[182:183], v[214:215]
	v_pk_fma_f32 v[64:65], v[64:65], v[184:185], v[216:217]
	v_pk_fma_f32 v[58:59], v[58:59], v[186:187], v[218:219]
	v_pk_fma_f32 v[60:61], v[60:61], v[188:189], v[220:221]
	v_pk_fma_f32 v[54:55], v[54:55], v[190:191], v[222:223]
	v_pk_fma_f32 v[56:57], v[56:57], v[192:193], v[224:225]
	v_pk_fma_f32 v[46:47], v[46:47], v[194:195], v[226:227]
	v_pk_fma_f32 v[48:49], v[48:49], v[196:197], v[228:229]
	global_store_dwordx4 v[158:159], v[62:65], off
	global_store_dwordx4 v[158:159], v[58:61], off offset:64
	global_store_dwordx4 v[158:159], v[54:57], off offset:512
	global_store_dwordx4 v[158:159], v[46:49], off offset:576
	s_mov_b64 s[38:39], 0xb0000
	v_lshl_add_u64 v[156:157], v[154:155], 0, s[38:39]
	global_load_dwordx4 v[214:217], v[156:157], off
	global_load_dwordx4 v[218:221], v[156:157], off offset:64
	global_load_dwordx4 v[222:225], v[156:157], off offset:512
	global_load_dwordx4 v[226:229], v[156:157], off offset:576
	s_waitcnt vmcnt(16)
	s_mov_b64 s[38:39], 0x90000
	v_lshl_add_u64 v[158:159], v[152:153], 0, s[38:39]
	v_pk_fma_f32 v[50:51], v[50:51], v[182:183], v[230:231]
	v_pk_fma_f32 v[52:53], v[52:53], v[184:185], v[232:233]
	v_pk_fma_f32 v[42:43], v[42:43], v[186:187], v[234:235]
	v_pk_fma_f32 v[44:45], v[44:45], v[188:189], v[236:237]
	v_pk_fma_f32 v[38:39], v[38:39], v[190:191], v[238:239]
	v_pk_fma_f32 v[40:41], v[40:41], v[192:193], v[240:241]
	v_pk_fma_f32 v[30:31], v[30:31], v[194:195], v[242:243]
	v_pk_fma_f32 v[32:33], v[32:33], v[196:197], v[244:245]
	global_store_dwordx4 v[158:159], v[50:53], off
	global_store_dwordx4 v[158:159], v[42:45], off offset:64
	global_store_dwordx4 v[158:159], v[38:41], off offset:512
	global_store_dwordx4 v[158:159], v[30:33], off offset:576
	s_waitcnt vmcnt(12)
	s_mov_b64 s[38:39], 0xa0000
	v_lshl_add_u64 v[158:159], v[152:153], 0, s[38:39]
	v_pk_fma_f32 v[34:35], v[34:35], v[182:183], v[198:199]
	v_pk_fma_f32 v[36:37], v[36:37], v[184:185], v[200:201]
	v_pk_fma_f32 v[26:27], v[26:27], v[186:187], v[202:203]
	v_pk_fma_f32 v[28:29], v[28:29], v[188:189], v[204:205]
	v_pk_fma_f32 v[22:23], v[22:23], v[190:191], v[206:207]
	v_pk_fma_f32 v[24:25], v[24:25], v[192:193], v[208:209]
	v_pk_fma_f32 v[14:15], v[14:15], v[194:195], v[210:211]
	v_pk_fma_f32 v[16:17], v[16:17], v[196:197], v[212:213]
	global_store_dwordx4 v[158:159], v[34:37], off
	global_store_dwordx4 v[158:159], v[26:29], off offset:64
	global_store_dwordx4 v[158:159], v[22:25], off offset:512
	global_store_dwordx4 v[158:159], v[14:17], off offset:576
	s_waitcnt vmcnt(8)
	s_mov_b64 s[38:39], 0xb0000
	v_lshl_add_u64 v[158:159], v[152:153], 0, s[38:39]
	v_pk_fma_f32 v[18:19], v[18:19], v[182:183], v[214:215]
	v_pk_fma_f32 v[20:21], v[20:21], v[184:185], v[216:217]
	v_pk_fma_f32 v[10:11], v[10:11], v[186:187], v[218:219]
	v_pk_fma_f32 v[12:13], v[12:13], v[188:189], v[220:221]
	v_pk_fma_f32 v[6:7], v[6:7], v[190:191], v[222:223]
	v_pk_fma_f32 v[8:9], v[8:9], v[192:193], v[224:225]
	v_pk_fma_f32 v[2:3], v[2:3], v[194:195], v[226:227]
	v_pk_fma_f32 v[4:5], v[4:5], v[196:197], v[228:229]
	global_store_dwordx4 v[158:159], v[18:21], off
	global_store_dwordx4 v[158:159], v[10:13], off offset:64
	global_store_dwordx4 v[158:159], v[6:9], off offset:512
	global_store_dwordx4 v[158:159], v[2:5], off offset:576
	s_mov_b32 s5, 0xb0000
	s_mov_b64 s[38:39], 0xb0000
	s_mov_b64 s[40:41], s[28:29]
	s_and_b64 vcc, exec, s[34:35]
	s_mov_b32 s38, s22
	s_cbranch_vccnz .LBB0_1096

;     __device__ __forceinline__ void operator()(const f32x4 (&acc)[2][2][4][2], const Unit& u, int wr, int wc, int fr, int fq) const {
;         const int b = u.pm / 33, tb = u.pm - b * 33;
;         const bool isctx = (tb == 0);
;         const float* gate = mod + (size_t)(isctx ? 4 : b) * 6144 + gidx * 1024;
;         const size_t row0 = isctx ? (size_t)b * CTX : (size_t)b * SEQ + (size_t)(tb - 1) * 256;
;         const float* src = isctx ? cin : xin; float* dst = isctx ? cout : xout;
;         const int col0 = u.pn * 256 + wc * 32 + 4 * fq;
; #pragma unroll
;         for (int ai = 0; ai < 2; ++ai)
; #pragma unroll
;             for (int m = 0; m < 4; ++m) {
;                 const size_t ro = (row0 + ai * 128 + wr * 64 + m * 16 + fr) * DM;
; #pragma unroll
;                 for (int bj = 0; bj < 2; ++bj)
; #pragma unroll
;                     for (int n = 0; n < 2; ++n) {
;                         const int c = col0 + bj * 128 + n * 16;
;                         const f32x4 gv = *(const f32x4*)(gate + c); const f32x4 xv = *(const f32x4*)(src + ro + c);
;                         *(f32x4*)(dst + ro + c) = xv + gv * acc[ai][bj][m][n];
;                     }
;                 asm volatile("" ::: "memory");
;             }
;     }
.LBB0_1280:
	s_add_u32 s26, s6, s38
	s_addc_u32 s27, s7, s39
	v_lshl_or_b32 v192, s54, 8, v141
	v_lshl_add_u64 v[156:157], v[146:147], 0, s[36:37]
	s_add_u32 s26, s26, 0x5000
	v_lshlrev_b64 v[156:157], 12, v[156:157]
	v_ashrrev_i32_e32 v193, 31, v192
	s_addc_u32 s27, s27, 0
	v_lshl_add_u64 v[158:159], s[28:29], 0, v[156:157]
	v_lshlrev_b64 v[156:157], 2, v[192:193]
	v_lshl_add_u64 v[160:161], s[26:27], 0, v[156:157]
	v_lshl_add_u64 v[194:195], v[158:159], 0, v[156:157]
	s_and_b64 vcc, exec, s[34:35]
	s_mov_b32 s54, s52
	s_mov_b32 s40, s53
	s_mov_b64 s[28:29], s[24:25]
	v_readlane_b32 s41, v254, 55
	v_mov_b32_e32 v152, v194
	v_mov_b32_e32 v153, v195
	global_load_dwordx4 v[184:187], v[160:161], off
	global_load_dwordx4 v[188:191], v[160:161], off offset:64
	global_load_dwordx4 v[192:195], v[160:161], off offset:512
	global_load_dwordx4 v[196:199], v[160:161], off offset:576
	global_load_dwordx4 v[200:203], v[152:153], off
	global_load_dwordx4 v[204:207], v[152:153], off offset:64
	global_load_dwordx4 v[208:211], v[152:153], off offset:512
	global_load_dwordx4 v[212:215], v[152:153], off offset:576
	s_mov_b64 s[26:27], 0x10000
	v_lshl_add_u64 v[154:155], v[152:153], 0, s[26:27]
	global_load_dwordx4 v[216:219], v[154:155], off
	global_load_dwordx4 v[220:223], v[154:155], off offset:64
	global_load_dwordx4 v[224:227], v[154:155], off offset:512
	global_load_dwordx4 v[228:231], v[154:155], off offset:576
	s_mov_b64 s[26:27], 0x20000
	v_lshl_add_u64 v[154:155], v[152:153], 0, s[26:27]
	global_load_dwordx4 v[232:235], v[154:155], off
	global_load_dwordx4 v[236:239], v[154:155], off offset:64
	global_load_dwordx4 v[240:243], v[154:155], off offset:512
	global_load_dwordx4 v[244:247], v[154:155], off offset:576
	s_waitcnt vmcnt(8)
	v_pk_fma_f32 v[126:127], v[126:127], v[184:185], v[200:201]
	v_pk_fma_f32 v[128:129], v[128:129], v[186:187], v[202:203]
	v_pk_fma_f32 v[122:123], v[122:123], v[188:189], v[204:205]
	v_pk_fma_f32 v[124:125], v[124:125], v[190:191], v[206:207]
	v_pk_fma_f32 v[118:119], v[118:119], v[192:193], v[208:209]
	v_pk_fma_f32 v[120:121], v[120:121], v[194:195], v[210:211]
	v_pk_fma_f32 v[114:115], v[114:115], v[196:197], v[212:213]
	v_pk_fma_f32 v[116:117], v[116:117], v[198:199], v[214:215]
	global_store_dwordx4 v[152:153], v[126:129], off
	global_store_dwordx4 v[152:153], v[122:125], off offset:64
	global_store_dwordx4 v[152:153], v[118:121], off offset:512
	global_store_dwordx4 v[152:153], v[114:117], off offset:576
	s_mov_b64 s[26:27], 0x30000
	v_lshl_add_u64 v[154:155], v[152:153], 0, s[26:27]
	global_load_dwordx4 v[200:203], v[154:155], off
	global_load_dwordx4 v[204:207], v[154:155], off offset:64
	global_load_dwordx4 v[208:211], v[154:155], off offset:512
	global_load_dwordx4 v[212:215], v[154:155], off offset:576
	s_waitcnt vmcnt(12)
	s_mov_b64 s[26:27], 0x10000
	v_lshl_add_u64 v[156:157], v[152:153], 0, s[26:27]
	v_pk_fma_f32 v[110:111], v[110:111], v[184:185], v[216:217]
	v_pk_fma_f32 v[112:113], v[112:113], v[186:187], v[218:219]
	v_pk_fma_f32 v[106:107], v[106:107], v[188:189], v[220:221]
	v_pk_fma_f32 v[108:109], v[108:109], v[190:191], v[222:223]
	v_pk_fma_f32 v[102:103], v[102:103], v[192:193], v[224:225]
	v_pk_fma_f32 v[104:105], v[104:105], v[194:195], v[226:227]
	v_pk_fma_f32 v[98:99], v[98:99], v[196:197], v[228:229]
	v_pk_fma_f32 v[100:101], v[100:101], v[198:199], v[230:231]
	global_store_dwordx4 v[156:157], v[110:113], off
	global_store_dwordx4 v[156:157], v[106:109], off offset:64
	global_store_dwordx4 v[156:157], v[102:105], off offset:512
	global_store_dwordx4 v[156:157], v[98:101], off offset:576
	s_mov_b64 s[26:27], 0x80000
	v_lshl_add_u64 v[154:155], v[152:153], 0, s[26:27]
	global_load_dwordx4 v[216:219], v[154:155], off
	global_load_dwordx4 v[220:223], v[154:155], off offset:64
	global_load_dwordx4 v[224:227], v[154:155], off offset:512
	global_load_dwordx4 v[228:231], v[154:155], off offset:576
	s_waitcnt vmcnt(16)
	s_mov_b64 s[26:27], 0x20000
	v_lshl_add_u64 v[156:157], v[152:153], 0, s[26:27]
	v_pk_fma_f32 v[94:95], v[94:95], v[184:185], v[232:233]
	v_pk_fma_f32 v[96:97], v[96:97], v[186:187], v[234:235]
	v_pk_fma_f32 v[90:91], v[90:91], v[188:189], v[236:237]
	v_pk_fma_f32 v[92:93], v[92:93], v[190:191], v[238:239]
	v_pk_fma_f32 v[86:87], v[86:87], v[192:193], v[240:241]
	v_pk_fma_f32 v[88:89], v[88:89], v[194:195], v[242:243]
	v_pk_fma_f32 v[82:83], v[82:83], v[196:197], v[244:245]
	v_pk_fma_f32 v[84:85], v[84:85], v[198:199], v[246:247]
	global_store_dwordx4 v[156:157], v[94:97], off
	global_store_dwordx4 v[156:157], v[90:93], off offset:64
	global_store_dwordx4 v[156:157], v[86:89], off offset:512
	global_store_dwordx4 v[156:157], v[82:85], off offset:576
	s_mov_b64 s[26:27], 0x90000
	v_lshl_add_u64 v[154:155], v[152:153], 0, s[26:27]
	global_load_dwordx4 v[232:235], v[154:155], off
	global_load_dwordx4 v[236:239], v[154:155], off offset:64
	global_load_dwordx4 v[240:243], v[154:155], off offset:512
	global_load_dwordx4 v[244:247], v[154:155], off offset:576
	s_waitcnt vmcnt(16)
;     __device__ __forceinline__ void operator()(const f32x4 (&acc)[2][2][4][2], const Unit& u, int wr, int wc, int fr, int fq) const {
;         const int b = u.pm / 33, tb = u.pm - b * 33;
;         const bool isctx = (tb == 0);
;         const float* gate = mod + (size_t)(isctx ? 4 : b) * 6144 + gidx * 1024;
;         const size_t row0 = isctx ? (size_t)b * CTX : (size_t)b * SEQ + (size_t)(tb - 1) * 256;
;         const float* src = isctx ? cin : xin; float* dst = isctx ? cout : xout;
;         const int col0 = u.pn * 256 + wc * 32 + 4 * fq;
; #pragma unroll
;         for (int ai = 0; ai < 2; ++ai)
; #pragma unroll
;             for (int m = 0; m < 4; ++m) {
;                 const size_t ro = (row0 + ai * 128 + wr * 64 + m * 16 + fr) * DM;
; #pragma unroll
;                 for (int bj = 0; bj < 2; ++bj)
; #pragma unroll
;                     for (int n = 0; n < 2; ++n) {
;                         const int c = col0 + bj * 128 + n * 16;
;                         const f32x4 gv = *(const f32x4*)(gate + c); const f32x4 xv = *(const f32x4*)(src + ro + c);
;                         *(f32x4*)(dst + ro + c) = xv + gv * acc[ai][bj][m][n];
;                     }
;                 asm volatile("" ::: "memory");
;             }
;     }
	s_mov_b64 s[26:27], 0x30000
	v_lshl_add_u64 v[156:157], v[152:153], 0, s[26:27]
	v_pk_fma_f32 v[78:79], v[78:79], v[184:185], v[200:201]
	v_pk_fma_f32 v[80:81], v[80:81], v[186:187], v[202:203]
	v_pk_fma_f32 v[74:75], v[74:75], v[188:189], v[204:205]
	v_pk_fma_f32 v[76:77], v[76:77], v[190:191], v[206:207]
	v_pk_fma_f32 v[70:71], v[70:71], v[192:193], v[208:209]
	v_pk_fma_f32 v[72:73], v[72:73], v[194:195], v[210:211]
	v_pk_fma_f32 v[66:67], v[66:67], v[196:197], v[212:213]
	v_pk_fma_f32 v[68:69], v[68:69], v[198:199], v[214:215]
	global_store_dwordx4 v[156:157], v[78:81], off
	global_store_dwordx4 v[156:157], v[74:77], off offset:64
	global_store_dwordx4 v[156:157], v[70:73], off offset:512
	global_store_dwordx4 v[156:157], v[66:69], off offset:576
	s_mov_b64 s[26:27], 0xa0000
	v_lshl_add_u64 v[154:155], v[152:153], 0, s[26:27]
	global_load_dwordx4 v[200:203], v[154:155], off
	global_load_dwordx4 v[204:207], v[154:155], off offset:64
	global_load_dwordx4 v[208:211], v[154:155], off offset:512
	global_load_dwordx4 v[212:215], v[154:155], off offset:576
	s_waitcnt vmcnt(16)
	s_mov_b64 s[26:27], 0x80000
	v_lshl_add_u64 v[156:157], v[152:153], 0, s[26:27]
	v_pk_fma_f32 v[62:63], v[62:63], v[184:185], v[216:217]
	v_pk_fma_f32 v[64:65], v[64:65], v[186:187], v[218:219]
	v_pk_fma_f32 v[58:59], v[58:59], v[188:189], v[220:221]
	v_pk_fma_f32 v[60:61], v[60:61], v[190:191], v[222:223]
	v_pk_fma_f32 v[54:55], v[54:55], v[192:193], v[224:225]
	v_pk_fma_f32 v[56:57], v[56:57], v[194:195], v[226:227]
	v_pk_fma_f32 v[50:51], v[50:51], v[196:197], v[228:229]
	v_pk_fma_f32 v[52:53], v[52:53], v[198:199], v[230:231]
	global_store_dwordx4 v[156:157], v[62:65], off
	global_store_dwordx4 v[156:157], v[58:61], off offset:64
	global_store_dwordx4 v[156:157], v[54:57], off offset:512
	global_store_dwordx4 v[156:157], v[50:53], off offset:576
	s_mov_b64 s[26:27], 0xb0000
	v_lshl_add_u64 v[154:155], v[152:153], 0, s[26:27]
	global_load_dwordx4 v[216:219], v[154:155], off
	global_load_dwordx4 v[220:223], v[154:155], off offset:64
	global_load_dwordx4 v[224:227], v[154:155], off offset:512
	global_load_dwordx4 v[228:231], v[154:155], off offset:576
	s_waitcnt vmcnt(16)
	s_mov_b64 s[26:27], 0x90000
	v_lshl_add_u64 v[156:157], v[152:153], 0, s[26:27]
	v_pk_fma_f32 v[46:47], v[46:47], v[184:185], v[232:233]
	v_pk_fma_f32 v[48:49], v[48:49], v[186:187], v[234:235]
	v_pk_fma_f32 v[42:43], v[42:43], v[188:189], v[236:237]
	v_pk_fma_f32 v[44:45], v[44:45], v[190:191], v[238:239]
	v_pk_fma_f32 v[38:39], v[38:39], v[192:193], v[240:241]
	v_pk_fma_f32 v[40:41], v[40:41], v[194:195], v[242:243]
	v_pk_fma_f32 v[34:35], v[34:35], v[196:197], v[244:245]
	v_pk_fma_f32 v[36:37], v[36:37], v[198:199], v[246:247]
	global_store_dwordx4 v[156:157], v[46:49], off
	global_store_dwordx4 v[156:157], v[42:45], off offset:64
	global_store_dwordx4 v[156:157], v[38:41], off offset:512
	global_store_dwordx4 v[156:157], v[34:37], off offset:576
	s_waitcnt vmcnt(12)
	s_mov_b64 s[26:27], 0xa0000
	v_lshl_add_u64 v[156:157], v[152:153], 0, s[26:27]
	v_pk_fma_f32 v[30:31], v[30:31], v[184:185], v[200:201]
	v_pk_fma_f32 v[32:33], v[32:33], v[186:187], v[202:203]
	v_pk_fma_f32 v[26:27], v[26:27], v[188:189], v[204:205]
	v_pk_fma_f32 v[28:29], v[28:29], v[190:191], v[206:207]
	v_pk_fma_f32 v[22:23], v[22:23], v[192:193], v[208:209]
	v_pk_fma_f32 v[24:25], v[24:25], v[194:195], v[210:211]
	v_pk_fma_f32 v[18:19], v[18:19], v[196:197], v[212:213]
	v_pk_fma_f32 v[20:21], v[20:21], v[198:199], v[214:215]
	global_store_dwordx4 v[156:157], v[30:33], off
	global_store_dwordx4 v[156:157], v[26:29], off offset:64
	global_store_dwordx4 v[156:157], v[22:25], off offset:512
	global_store_dwordx4 v[156:157], v[18:21], off offset:576
	s_waitcnt vmcnt(8)
	s_mov_b64 s[26:27], 0xb0000
	v_lshl_add_u64 v[156:157], v[152:153], 0, s[26:27]
	v_pk_fma_f32 v[14:15], v[14:15], v[184:185], v[216:217]
	v_pk_fma_f32 v[16:17], v[16:17], v[186:187], v[218:219]
	v_pk_fma_f32 v[10:11], v[10:11], v[188:189], v[220:221]
	v_pk_fma_f32 v[12:13], v[12:13], v[190:191], v[222:223]
	v_pk_fma_f32 v[6:7], v[6:7], v[192:193], v[224:225]
	v_pk_fma_f32 v[8:9], v[8:9], v[194:195], v[226:227]
	v_pk_fma_f32 v[2:3], v[2:3], v[196:197], v[228:229]
	v_pk_fma_f32 v[4:5], v[4:5], v[198:199], v[230:231]
	global_store_dwordx4 v[156:157], v[14:17], off
	global_store_dwordx4 v[156:157], v[10:13], off offset:64
	global_store_dwordx4 v[156:157], v[6:9], off offset:512
	global_store_dwordx4 v[156:157], v[2:5], off offset:576
	s_mov_b64 s[26:27], s[22:23]
	s_cbranch_vccnz .LBB0_1289
